# attention softmax: row-max exchange between wave halves via v_permlane32_swap instead of a ds_bpermute round trip
# speedup vs baseline: 1.0103x; 1.0103x over previous
.LBB0_546:
	s_setprio 1
	ds_read_b128 v[66:69], v183
	s_waitcnt lgkmcnt(0)
	v_mfma_f32_32x32x16_bf16 v[82:97], v[66:69], v[98:101], 0
	ds_read_b128 v[66:69], v183 offset:32
	s_waitcnt lgkmcnt(0)
	v_mfma_f32_32x32x16_bf16 v[82:97], v[66:69], v[102:105], v[82:97]
	ds_read_b128 v[66:69], v183 offset:64
	s_waitcnt lgkmcnt(0)
	v_mfma_f32_32x32x16_bf16 v[82:97], v[66:69], v[106:109], v[82:97]
	ds_read_b128 v[66:69], v183 offset:96
	s_waitcnt lgkmcnt(0)
	v_mfma_f32_32x32x16_bf16 v[82:97], v[66:69], v[110:113], v[82:97]
	ds_read_b128 v[66:69], v183 offset:128
	s_waitcnt lgkmcnt(0)
	v_mfma_f32_32x32x16_bf16 v[82:97], v[66:69], v[126:129], v[82:97]
	ds_read_b128 v[66:69], v183 offset:160
	s_waitcnt lgkmcnt(0)
	v_mfma_f32_32x32x16_bf16 v[82:97], v[66:69], v[114:117], v[82:97]
	ds_read_b128 v[66:69], v183 offset:192
	s_waitcnt lgkmcnt(0)
	v_mfma_f32_32x32x16_bf16 v[82:97], v[66:69], v[122:125], v[82:97]
	ds_read_b128 v[66:69], v183 offset:224
	s_waitcnt lgkmcnt(0)
	v_mfma_f32_32x32x16_bf16 v[82:97], v[66:69], v[118:121], v[82:97]
	ds_read_b128 v[66:69], v183 offset:8704
	ds_read_b128 v[186:189], v183 offset:8736
	s_waitcnt lgkmcnt(0)
	v_mfma_f32_32x32x16_bf16 v[66:81], v[66:69], v[98:101], 0
	v_mfma_f32_32x32x16_bf16 v[66:81], v[186:189], v[102:105], v[66:81]
	ds_read_b128 v[186:189], v183 offset:8768
	s_waitcnt lgkmcnt(0)
	v_mfma_f32_32x32x16_bf16 v[66:81], v[186:189], v[106:109], v[66:81]
	ds_read_b128 v[186:189], v183 offset:8800
	s_waitcnt lgkmcnt(0)
	v_mfma_f32_32x32x16_bf16 v[66:81], v[186:189], v[110:113], v[66:81]
	ds_read_b128 v[186:189], v183 offset:8832
	s_waitcnt lgkmcnt(0)
	v_mfma_f32_32x32x16_bf16 v[66:81], v[186:189], v[126:129], v[66:81]
	ds_read_b128 v[186:189], v183 offset:8864
	s_waitcnt lgkmcnt(0)
	v_mfma_f32_32x32x16_bf16 v[66:81], v[186:189], v[114:117], v[66:81]
	ds_read_b128 v[186:189], v183 offset:8896
	s_waitcnt lgkmcnt(0)
	v_mfma_f32_32x32x16_bf16 v[66:81], v[186:189], v[122:125], v[66:81]
	ds_read_b128 v[186:189], v183 offset:8928
	s_waitcnt lgkmcnt(0)
	v_mfma_f32_32x32x16_bf16 v[66:81], v[186:189], v[118:121], v[66:81]
	s_setprio 0
	v_add_u32_e32 v0, s9, v148
	v_sub_u32_e32 v186, v150, v0
	v_cmp_gt_u32_e32 vcc, s89, v186
	v_mul_f32_e32 v82, 0x3e0293ee, v82
	s_and_b64 vcc, s[38:39], vcc
	v_sub_u32_e32 v186, v0, v150
	v_cndmask_b32_e32 v82, v82, v226, vcc
	v_cmp_lt_u32_e32 vcc, s59, v186
	v_mul_f32_e32 v83, 0x3e0293ee, v83
	s_and_b64 vcc, s[38:39], vcc
	v_sub_u32_e32 v187, v151, v0
	v_cndmask_b32_e32 v83, v83, v226, vcc
	v_cmp_gt_u32_e32 vcc, s89, v187
	v_mul_f32_e32 v84, 0x3e0293ee, v84
	s_and_b64 vcc, s[38:39], vcc
	v_sub_u32_e32 v187, v152, v0
	v_cndmask_b32_e32 v84, v84, v226, vcc
	v_cmp_gt_u32_e32 vcc, s89, v187
	v_mul_f32_e32 v85, 0x3e0293ee, v85
	s_and_b64 vcc, s[38:39], vcc
	v_sub_u32_e32 v187, v153, v0
	v_cndmask_b32_e32 v85, v85, v226, vcc
	v_cmp_gt_u32_e32 vcc, s89, v187
	v_mul_f32_e32 v86, 0x3e0293ee, v86
	s_and_b64 vcc, s[38:39], vcc
	v_sub_u32_e32 v187, v154, v0
	v_cndmask_b32_e32 v86, v86, v226, vcc
	v_cmp_gt_u32_e32 vcc, s89, v187
	v_mul_f32_e32 v87, 0x3e0293ee, v87
	s_and_b64 vcc, s[38:39], vcc
	v_sub_u32_e32 v187, v155, v0
	v_cndmask_b32_e32 v87, v87, v226, vcc
	v_cmp_gt_u32_e32 vcc, s89, v187
	v_mul_f32_e32 v88, 0x3e0293ee, v88
	s_and_b64 vcc, s[38:39], vcc
	v_sub_u32_e32 v187, v156, v0
	v_cndmask_b32_e32 v88, v88, v226, vcc
	v_cmp_gt_u32_e32 vcc, s89, v187
	v_mul_f32_e32 v89, 0x3e0293ee, v89
	s_and_b64 vcc, s[38:39], vcc
	v_sub_u32_e32 v187, v157, v0
	v_cndmask_b32_e32 v89, v89, v226, vcc
	v_cmp_gt_u32_e32 vcc, s89, v187
	v_mul_f32_e32 v90, 0x3e0293ee, v90
	s_and_b64 vcc, s[38:39], vcc
	v_sub_u32_e32 v187, v158, v0
	v_cndmask_b32_e32 v90, v90, v226, vcc
	v_cmp_gt_u32_e32 vcc, s89, v187
	v_mul_f32_e32 v91, 0x3e0293ee, v91
	s_and_b64 vcc, s[38:39], vcc
	v_sub_u32_e32 v187, v159, v0
	v_cndmask_b32_e32 v91, v91, v226, vcc
	v_cmp_gt_u32_e32 vcc, s89, v187
	v_mul_f32_e32 v92, 0x3e0293ee, v92
	s_and_b64 vcc, s[38:39], vcc
	v_sub_u32_e32 v187, v160, v0
	v_cndmask_b32_e32 v92, v92, v226, vcc
	v_cmp_gt_u32_e32 vcc, s89, v187
	v_mul_f32_e32 v93, 0x3e0293ee, v93
	s_and_b64 vcc, s[38:39], vcc
	v_sub_u32_e32 v187, v161, v0
	v_cndmask_b32_e32 v93, v93, v226, vcc
	v_cmp_gt_u32_e32 vcc, s89, v187
	v_mul_f32_e32 v94, 0x3e0293ee, v94
	s_and_b64 vcc, s[38:39], vcc
	v_sub_u32_e32 v187, v162, v0
	v_cndmask_b32_e32 v94, v94, v226, vcc
	v_cmp_gt_u32_e32 vcc, s89, v187
	v_mul_f32_e32 v95, 0x3e0293ee, v95
	s_and_b64 vcc, s[38:39], vcc
	v_sub_u32_e32 v187, v163, v0
	v_cndmask_b32_e32 v95, v95, v226, vcc
	v_cmp_gt_u32_e32 vcc, s89, v187
	s_mov_b32 s6, 0xff61b1e6
	v_mul_f32_e32 v96, 0x3e0293ee, v96
	s_and_b64 vcc, s[38:39], vcc
	v_sub_u32_e32 v187, v164, v0
	v_max3_f32 v186, v82, s6, v83
	v_cndmask_b32_e32 v96, v96, v226, vcc
	v_cmp_gt_u32_e32 vcc, s89, v187
	v_max3_f32 v186, v186, v84, v85
	v_mul_f32_e32 v97, 0x3e0293ee, v97
	s_and_b64 vcc, s[38:39], vcc
	v_sub_u32_e32 v187, v165, v0
	v_max3_f32 v186, v186, v86, v87
	v_cndmask_b32_e32 v97, v97, v226, vcc
	v_cmp_gt_u32_e32 vcc, s89, v187
	v_max3_f32 v186, v186, v88, v89
	v_mul_f32_e32 v66, 0x3e0293ee, v66
	s_and_b64 vcc, s[38:39], vcc
	v_max3_f32 v186, v186, v90, v91
	v_cndmask_b32_e32 v187, v66, v226, vcc
	v_mul_f32_e32 v66, 0x3e0293ee, v67
	v_sub_u32_e32 v67, v166, v0
	v_max3_f32 v186, v186, v92, v93
	v_cmp_gt_u32_e32 vcc, s89, v67
	v_max3_f32 v186, v186, v94, v95
	s_and_b64 vcc, s[38:39], vcc
	v_max3_f32 v186, v186, v96, v97
	v_cndmask_b32_e32 v67, v66, v226, vcc
	v_max3_f32 v66, v186, v187, v67
	v_sub_u32_e32 v186, v167, v0
	v_cmp_gt_u32_e32 vcc, s89, v186
	v_mul_f32_e32 v68, 0x3e0293ee, v68
	s_and_b64 vcc, s[38:39], vcc
	v_sub_u32_e32 v186, v168, v0
	v_cndmask_b32_e32 v68, v68, v226, vcc
	v_cmp_gt_u32_e32 vcc, s89, v186
	v_mul_f32_e32 v69, 0x3e0293ee, v69
	s_and_b64 vcc, s[38:39], vcc
	v_sub_u32_e32 v186, v169, v0
	v_cndmask_b32_e32 v69, v69, v226, vcc
	v_cmp_gt_u32_e32 vcc, s89, v186
	v_mul_f32_e32 v70, 0x3e0293ee, v70
	s_and_b64 vcc, s[38:39], vcc
	v_sub_u32_e32 v186, v170, v0
	v_cndmask_b32_e32 v70, v70, v226, vcc
	v_cmp_gt_u32_e32 vcc, s89, v186
	v_mul_f32_e32 v71, 0x3e0293ee, v71
	s_and_b64 vcc, s[38:39], vcc
	v_sub_u32_e32 v186, v171, v0
	v_cndmask_b32_e32 v71, v71, v226, vcc
	v_cmp_gt_u32_e32 vcc, s89, v186
	v_mul_f32_e32 v72, 0x3e0293ee, v72
	s_and_b64 vcc, s[38:39], vcc
	v_sub_u32_e32 v186, v172, v0
	v_cndmask_b32_e32 v72, v72, v226, vcc
	v_cmp_gt_u32_e32 vcc, s89, v186
	v_mul_f32_e32 v73, 0x3e0293ee, v73
	s_and_b64 vcc, s[38:39], vcc
	v_sub_u32_e32 v186, v173, v0
	v_cndmask_b32_e32 v73, v73, v226, vcc
	v_cmp_gt_u32_e32 vcc, s89, v186
	v_mul_f32_e32 v74, 0x3e0293ee, v74
	s_and_b64 vcc, s[38:39], vcc
	v_sub_u32_e32 v186, v174, v0
	v_cndmask_b32_e32 v74, v74, v226, vcc
	v_cmp_gt_u32_e32 vcc, s89, v186
	v_mul_f32_e32 v75, 0x3e0293ee, v75
	s_and_b64 vcc, s[38:39], vcc
	v_sub_u32_e32 v186, v175, v0
	v_cndmask_b32_e32 v75, v75, v226, vcc
	v_cmp_gt_u32_e32 vcc, s89, v186
	v_mul_f32_e32 v76, 0x3e0293ee, v76
	s_and_b64 vcc, s[38:39], vcc
	v_sub_u32_e32 v186, v176, v0
	v_cndmask_b32_e32 v76, v76, v226, vcc
	v_cmp_gt_u32_e32 vcc, s89, v186
	v_mul_f32_e32 v77, 0x3e0293ee, v77
	s_and_b64 vcc, s[38:39], vcc
	v_sub_u32_e32 v186, v177, v0
	v_cndmask_b32_e32 v77, v77, v226, vcc
	v_cmp_gt_u32_e32 vcc, s89, v186
	v_mul_f32_e32 v78, 0x3e0293ee, v78
	s_and_b64 vcc, s[38:39], vcc
	v_sub_u32_e32 v186, v178, v0
	v_cndmask_b32_e32 v78, v78, v226, vcc
	v_cmp_gt_u32_e32 vcc, s89, v186
	v_mul_f32_e32 v79, 0x3e0293ee, v79
	s_and_b64 vcc, s[38:39], vcc
	v_sub_u32_e32 v186, v179, v0
	v_cndmask_b32_e32 v79, v79, v226, vcc
	v_cmp_gt_u32_e32 vcc, s89, v186
	v_max3_f32 v66, v66, v68, v69
	v_mul_f32_e32 v80, 0x3e0293ee, v80
	s_and_b64 vcc, s[38:39], vcc
	v_sub_u32_e32 v0, v180, v0
	v_max3_f32 v66, v66, v70, v71
	v_cndmask_b32_e32 v80, v80, v226, vcc
	v_cmp_gt_u32_e32 vcc, s89, v0
	v_max3_f32 v66, v66, v72, v73
	v_mul_f32_e32 v81, 0x3e0293ee, v81
	s_and_b64 vcc, s[38:39], vcc
	v_and_b32_e32 v186, 64, v223
	v_max3_f32 v66, v66, v74, v75
	v_cndmask_b32_e32 v0, v81, v226, vcc
	v_xor_b32_e32 v81, 32, v223
	v_add_u32_e32 v186, 64, v186
	v_max3_f32 v66, v66, v76, v77
	v_cmp_lt_i32_e32 vcc, v81, v186
	v_max3_f32 v66, v66, v78, v79
	v_max3_f32 v66, v66, v80, v0
	v_cndmask_b32_e32 v81, v223, v81, vcc
	v_lshlrev_b32_e32 v81, 2, v81
	v_mov_b32_e32 v186, v66
	s_nop 1
	v_permlane32_swap_b32_e32 v66, v186
	s_waitcnt lgkmcnt(0)
	v_max3_f32 v66, v185, v66, v186
	v_sub_f32_e32 v82, v82, v66
	v_exp_f32_e32 v82, v82
	v_sub_f32_e32 v83, v83, v66
	v_exp_f32_e32 v83, v83
	v_sub_f32_e32 v84, v84, v66
	v_exp_f32_e32 v84, v84
	v_sub_f32_e32 v85, v85, v66
	v_exp_f32_e32 v85, v85
	v_sub_f32_e32 v86, v86, v66
	v_add_f32_e32 v186, 0, v82
	v_exp_f32_e32 v86, v86
	v_sub_f32_e32 v87, v87, v66
	v_add_f32_e32 v186, v83, v186
	v_exp_f32_e32 v87, v87
	v_sub_f32_e32 v88, v88, v66
	v_add_f32_e32 v186, v84, v186
	v_exp_f32_e32 v88, v88
	v_sub_f32_e32 v89, v89, v66
	v_add_f32_e32 v186, v85, v186
	v_exp_f32_e32 v89, v89
	v_sub_f32_e32 v90, v90, v66
	v_add_f32_e32 v186, v86, v186
	v_exp_f32_e32 v90, v90
	v_sub_f32_e32 v91, v91, v66
	v_add_f32_e32 v186, v87, v186
	v_exp_f32_e32 v91, v91
	v_sub_f32_e32 v92, v92, v66
	v_add_f32_e32 v186, v88, v186
	v_exp_f32_e32 v92, v92
	v_sub_f32_e32 v93, v93, v66
	v_add_f32_e32 v186, v89, v186
	v_exp_f32_e32 v93, v93
	v_sub_f32_e32 v94, v94, v66
	v_add_f32_e32 v186, v90, v186
	v_exp_f32_e32 v94, v94
	v_sub_f32_e32 v95, v95, v66
	v_add_f32_e32 v186, v91, v186
	v_exp_f32_e32 v95, v95
	v_sub_f32_e32 v96, v96, v66
	v_add_f32_e32 v186, v92, v186
	v_exp_f32_e32 v96, v96
	v_sub_f32_e32 v97, v97, v66
	v_add_f32_e32 v186, v93, v186
	v_exp_f32_e32 v97, v97
	v_sub_f32_e32 v187, v187, v66
	v_add_f32_e32 v186, v94, v186
	v_exp_f32_e32 v187, v187
	v_sub_f32_e32 v67, v67, v66
	v_add_f32_e32 v186, v95, v186
	v_exp_f32_e32 v67, v67
	v_sub_f32_e32 v68, v68, v66
	v_add_f32_e32 v186, v96, v186
	v_exp_f32_e32 v188, v68
	v_sub_f32_e32 v68, v69, v66
	v_add_f32_e32 v186, v97, v186
	v_exp_f32_e32 v189, v68
	v_sub_f32_e32 v68, v70, v66
	v_add_f32_e32 v186, v187, v186
	v_exp_f32_e32 v190, v68
	v_sub_f32_e32 v69, v71, v66
	v_add_f32_e32 v68, v67, v186
	v_exp_f32_e32 v186, v69
	v_sub_f32_e32 v69, v72, v66
	v_add_f32_e32 v68, v188, v68
	v_exp_f32_e32 v191, v69
	v_sub_f32_e32 v69, v73, v66
	v_add_f32_e32 v68, v189, v68
	v_exp_f32_e32 v192, v69
	v_sub_f32_e32 v69, v74, v66
	v_add_f32_e32 v68, v190, v68
	v_exp_f32_e32 v193, v69
	v_sub_f32_e32 v69, v75, v66
	v_add_f32_e32 v68, v186, v68
	v_exp_f32_e32 v194, v69
	v_sub_f32_e32 v69, v76, v66
	v_add_f32_e32 v68, v191, v68
	v_exp_f32_e32 v76, v69
	v_sub_f32_e32 v69, v77, v66
	v_add_f32_e32 v68, v192, v68
	v_exp_f32_e32 v77, v69
	v_sub_f32_e32 v69, v78, v66
	v_add_f32_e32 v68, v193, v68
	v_exp_f32_e32 v78, v69
	v_sub_f32_e32 v69, v79, v66
	v_add_f32_e32 v68, v194, v68
	v_exp_f32_e32 v79, v69
	v_sub_f32_e32 v69, v80, v66
	v_add_f32_e32 v68, v76, v68
	v_exp_f32_e32 v80, v69
	v_sub_f32_e32 v0, v0, v66
	v_add_f32_e32 v68, v77, v68
	v_exp_f32_e32 v195, v0
	v_add_f32_e32 v68, v78, v68
	v_add_f32_e32 v68, v79, v68
	v_add_f32_e32 v68, v80, v68
	v_sub_f32_e32 v185, v185, v66
	v_add_f32_e32 v68, v195, v68
	v_exp_f32_e32 v0, v185
	ds_bpermute_b32 v69, v81, v68
	v_pk_mul_f32 v[64:65], v[64:65], v[0:1] op_sel_hi:[1,0]
	v_pk_mul_f32 v[62:63], v[62:63], v[0:1] op_sel_hi:[1,0]
	v_pk_mul_f32 v[60:61], v[60:61], v[0:1] op_sel_hi:[1,0]
	v_pk_mul_f32 v[58:59], v[58:59], v[0:1] op_sel_hi:[1,0]
	v_pk_mul_f32 v[56:57], v[56:57], v[0:1] op_sel_hi:[1,0]
	v_pk_mul_f32 v[54:55], v[54:55], v[0:1] op_sel_hi:[1,0]
	v_pk_mul_f32 v[52:53], v[52:53], v[0:1] op_sel_hi:[1,0]
	v_pk_mul_f32 v[50:51], v[50:51], v[0:1] op_sel_hi:[1,0]
	v_pk_mul_f32 v[48:49], v[48:49], v[0:1] op_sel_hi:[1,0]
	v_pk_mul_f32 v[46:47], v[46:47], v[0:1] op_sel_hi:[1,0]
	v_pk_mul_f32 v[44:45], v[44:45], v[0:1] op_sel_hi:[1,0]
	v_pk_mul_f32 v[42:43], v[42:43], v[0:1] op_sel_hi:[1,0]
	v_pk_mul_f32 v[40:41], v[40:41], v[0:1] op_sel_hi:[1,0]
	v_pk_mul_f32 v[38:39], v[38:39], v[0:1] op_sel_hi:[1,0]
	v_pk_mul_f32 v[36:37], v[36:37], v[0:1] op_sel_hi:[1,0]
	v_pk_mul_f32 v[34:35], v[34:35], v[0:1] op_sel_hi:[1,0]
	v_pk_mul_f32 v[32:33], v[32:33], v[0:1] op_sel_hi:[1,0]
	v_pk_mul_f32 v[30:31], v[30:31], v[0:1] op_sel_hi:[1,0]
	v_pk_mul_f32 v[28:29], v[28:29], v[0:1] op_sel_hi:[1,0]
	v_pk_mul_f32 v[26:27], v[26:27], v[0:1] op_sel_hi:[1,0]
	v_pk_mul_f32 v[24:25], v[24:25], v[0:1] op_sel_hi:[1,0]
	v_pk_mul_f32 v[22:23], v[22:23], v[0:1] op_sel_hi:[1,0]
	v_pk_mul_f32 v[20:21], v[20:21], v[0:1] op_sel_hi:[1,0]
	v_pk_mul_f32 v[18:19], v[18:19], v[0:1] op_sel_hi:[1,0]
	v_pk_mul_f32 v[16:17], v[16:17], v[0:1] op_sel_hi:[1,0]
	v_pk_mul_f32 v[14:15], v[14:15], v[0:1] op_sel_hi:[1,0]
	v_pk_mul_f32 v[12:13], v[12:13], v[0:1] op_sel_hi:[1,0]
	v_pk_mul_f32 v[10:11], v[10:11], v[0:1] op_sel_hi:[1,0]
	v_pk_mul_f32 v[8:9], v[8:9], v[0:1] op_sel_hi:[1,0]
	v_pk_mul_f32 v[6:7], v[6:7], v[0:1] op_sel_hi:[1,0]
	v_pk_mul_f32 v[4:5], v[4:5], v[0:1] op_sel_hi:[1,0]
	v_pk_mul_f32 v[2:3], v[2:3], v[0:1] op_sel_hi:[1,0]
	s_waitcnt lgkmcnt(0)
	v_add_f32_e32 v81, v68, v69
	s_setprio 1
	v_cvt_pk_bf16_f32 v68, v82, v83
	v_add_u32_e32 v82, 0x4000, v184
	ds_read2_b64 v[72:75], v82 offset0:128 offset1:130
	v_cvt_pk_bf16_f32 v69, v84, v85
	v_cvt_pk_bf16_f32 v70, v86, v87
	v_cvt_pk_bf16_f32 v71, v88, v89
	v_add_u32_e32 v83, 0x5000, v184
	v_add_u32_e32 v84, 0x6800, v184
	v_add_u32_e32 v85, 0x7800, v184
	s_waitcnt lgkmcnt(0)
	v_mfma_f32_32x32x16_bf16 v[50:65], v[72:75], v[68:71], v[50:65]
	ds_read2_b64 v[72:75], v83 offset0:192 offset1:194
	s_waitcnt lgkmcnt(0)
	v_mfma_f32_32x32x16_bf16 v[34:49], v[72:75], v[68:71], v[34:49]
	ds_read2_b64 v[72:75], v84 offset1:2
	s_waitcnt lgkmcnt(0)
	v_mfma_f32_32x32x16_bf16 v[18:33], v[72:75], v[68:71], v[18:33]
	ds_read2_b64 v[72:75], v85 offset0:64 offset1:66
	s_waitcnt lgkmcnt(0)
	v_mfma_f32_32x32x16_bf16 v[2:17], v[72:75], v[68:71], v[2:17]
	ds_read2_b64 v[72:75], v82 offset0:132 offset1:134
	v_cvt_pk_bf16_f32 v68, v90, v91
	v_cvt_pk_bf16_f32 v69, v92, v93
	v_cvt_pk_bf16_f32 v70, v94, v95
	v_cvt_pk_bf16_f32 v71, v96, v97
	s_waitcnt lgkmcnt(0)
	s_nop 0
	v_mfma_f32_32x32x16_bf16 v[50:65], v[72:75], v[68:71], v[50:65]
	ds_read2_b64 v[72:75], v83 offset0:196 offset1:198
	s_waitcnt lgkmcnt(0)
	v_mfma_f32_32x32x16_bf16 v[34:49], v[72:75], v[68:71], v[34:49]
	ds_read2_b64 v[72:75], v84 offset0:4 offset1:6
	s_waitcnt lgkmcnt(0)
	v_mfma_f32_32x32x16_bf16 v[18:33], v[72:75], v[68:71], v[18:33]
	ds_read2_b64 v[72:75], v85 offset0:68 offset1:70
	s_waitcnt lgkmcnt(0)
	v_mfma_f32_32x32x16_bf16 v[2:17], v[72:75], v[68:71], v[2:17]
	ds_read2_b64 v[72:75], v82 offset0:136 offset1:138
	v_cvt_pk_bf16_f32 v68, v187, v67
	v_cvt_pk_bf16_f32 v69, v188, v189
	v_cvt_pk_bf16_f32 v70, v190, v186
	v_cvt_pk_bf16_f32 v71, v191, v192
	s_waitcnt lgkmcnt(0)
	s_nop 0
	v_mfma_f32_32x32x16_bf16 v[50:65], v[72:75], v[68:71], v[50:65]
	ds_read2_b64 v[72:75], v83 offset0:200 offset1:202
	s_waitcnt lgkmcnt(0)
	v_mfma_f32_32x32x16_bf16 v[34:49], v[72:75], v[68:71], v[34:49]
	ds_read2_b64 v[72:75], v84 offset0:8 offset1:10
	s_waitcnt lgkmcnt(0)
	v_mfma_f32_32x32x16_bf16 v[18:33], v[72:75], v[68:71], v[18:33]
	ds_read2_b64 v[72:75], v85 offset0:72 offset1:74
	s_waitcnt lgkmcnt(0)
	v_mfma_f32_32x32x16_bf16 v[2:17], v[72:75], v[68:71], v[2:17]
	ds_read2_b64 v[72:75], v82 offset0:140 offset1:142
	v_cvt_pk_bf16_f32 v68, v193, v194
	v_cvt_pk_bf16_f32 v69, v76, v77
	v_cvt_pk_bf16_f32 v70, v78, v79
	v_cvt_pk_bf16_f32 v71, v80, v195
	s_waitcnt lgkmcnt(0)
	s_nop 0
	v_mfma_f32_32x32x16_bf16 v[50:65], v[72:75], v[68:71], v[50:65]
	ds_read2_b64 v[72:75], v83 offset0:204 offset1:206
	s_waitcnt lgkmcnt(0)
	v_mfma_f32_32x32x16_bf16 v[34:49], v[72:75], v[68:71], v[34:49]
	ds_read2_b64 v[72:75], v84 offset0:12 offset1:14
	s_waitcnt lgkmcnt(0)
	v_mfma_f32_32x32x16_bf16 v[18:33], v[72:75], v[68:71], v[18:33]
	ds_read2_b64 v[72:75], v85 offset0:76 offset1:78
	s_waitcnt lgkmcnt(0)
	v_mfma_f32_32x32x16_bf16 v[2:17], v[72:75], v[68:71], v[2:17]
	v_fmac_f32_e32 v81, v149, v0
	s_setprio 0
	v_mov_b32_e32 v149, v81
	v_mov_b32_e32 v185, v66
	s_add_i32 s68, s68, 64
	s_cmp_lg_u32 s71, s8
	s_cbranch_scc0 .LBB0_476
